# drop duplicate B half-tile LDS-DMA loads in the three 256x128-tile GEMM instances (counted waits re-derived) + S5 staging unrolled
# speedup vs baseline: 1.0602x; 1.0231x over previous
.LBB0_106:
	v_readlane_b32 s4, v239, 47
	v_readlane_b32 s5, v239, 48
	s_lshl_b64 s[4:5], s[4:5], 21
	s_add_u32 s4, s34, s4
	s_addc_u32 s5, s35, s5
	s_add_u32 s65, s4, 0x2300000
	s_addc_u32 s86, s5, 0
	s_ashr_i32 s3, s3, 3
	s_add_i32 s3, s9, s3
	s_ashr_i32 s4, s3, 31
	s_lshr_b32 s4, s4, 24
	s_add_i32 s4, s3, s4
	s_ashr_i32 s5, s4, 8
	s_and_b32 s4, s4, 0xffffff00
	s_sub_i32 s3, s3, s4
	s_sext_i32_i16 s4, s3
	s_bfe_u32 s4, s4, 0x60019
	s_add_i32 s4, s3, s4
	s_sub_i32 s56, 0, s5
	s_sext_i32_i16 s5, s4
	s_and_b32 s4, s4, 0xffc0
	s_sub_i32 s3, s3, s4
	s_bfe_i32 s4, s3, 0x80000
	s_bfe_u32 s4, s4, 0x3000c
	s_add_i32 s4, s3, s4
	s_bfe_i32 s9, s4, 0x80000
	s_and_b32 s4, s4, 0xf8
	s_ashr_i32 s5, s5, 6
	s_sub_i32 s3, s3, s4
	s_lshl_b32 s5, s5, 3
	s_sext_i32_i8 s3, s3
	s_add_i32 s70, s5, s3
	s_ashr_i32 s11, s15, 6
	s_sext_i32_i16 s9, s9
	s_ashr_i32 s71, s70, 31
	s_ashr_i32 s14, s15, 8
	s_lshl_b32 s8, s11, 10
	s_lshr_b32 s10, s9, 3
	s_lshl_b64 s[12:13], s[56:57], 11
	s_lshl_b64 s[4:5], s[70:71], 19
	s_add_u32 s3, s81, s12
	s_addc_u32 s9, s88, s13
	s_add_u32 s4, s3, s4
	s_addc_u32 s5, s9, s5
	s_waitcnt lgkmcnt(0)
	s_bfe_i64 s[18:19], s[10:11], 0x100000
	s_lshl_b64 s[18:19], s[18:19], 18
	s_add_u32 s3, s65, s12
	s_addc_u32 s9, s86, s13
	s_add_u32 s72, s3, s18
	s_addc_u32 s73, s9, s19
	s_add_i32 s9, s8, 0
	s_add_i32 m0, s9, 0x10000
	s_add_i32 s71, s9, 0x14000
	global_load_lds_dwordx4 v164, s[72:73]
	s_add_i32 m0, s9, 0x12000
	s_add_i32 s12, s9, 0x16000
	global_load_lds_dwordx4 v152, s[72:73]
	s_add_i32 s13, s9, 0x2000
	s_add_u32 s18, s4, 0x40000
	s_mov_b32 m0, s9
	s_addc_u32 s19, s5, 0
	global_load_lds_dwordx4 v164, s[4:5]
	s_mov_b32 m0, s13
	s_add_i32 s89, s9, 0x4000
	global_load_lds_dwordx4 v152, s[4:5]
	s_mov_b32 m0, s89
	s_add_i32 s3, s9, 0x6000
	global_load_lds_dwordx4 v164, s[18:19]
	s_mov_b32 m0, s3
	s_cmp_eq_u32 s14, 1
	global_load_lds_dwordx4 v152, s[18:19]
	v_mov_b32_e32 v153, v165
	s_cselect_b64 s[18:19], -1, 0
	v_lshl_add_u64 v[6:7], s[72:73], 0, v[164:165]
	v_lshl_add_u64 v[4:5], s[72:73], 0, v[152:153]
	v_lshl_add_u64 v[0:1], s[4:5], 0, v[164:165]
	v_writelane_b32 v238, s18, 9
	s_cmp_lg_u32 s14, 1
	v_lshl_add_u64 v[2:3], s[4:5], 0, v[152:153]
	v_writelane_b32 v238, s19, 10
	s_cbranch_scc1 .LBB0_108
	s_barrier
.LBB0_108:
	v_readlane_b32 s18, v239, 51
	v_readlane_b32 s19, v239, 52
	s_add_u32 s87, s18, 0x2000
	s_sext_i32_i8 s33, s10
	s_addc_u32 s10, s19, 0
	v_readlane_b32 s18, v239, 47
	v_readlane_b32 s19, v239, 48
	s_lshl_b32 s18, s18, 10
	s_ashr_i32 s19, s18, 31
	s_lshl_b64 s[18:19], s[18:19], 2
	s_add_u32 s82, s46, s18
	v_writelane_b32 v240, s10, 62
	s_addc_u32 s83, s47, s19
	s_lshl_b32 s10, s14, 6
	v_lshlrev_b32_e32 v9, 2, v94
	v_writelane_b32 v239, s10, 60
	s_lshl_b32 s10, s14, 13
	v_lshl_or_b32 v8, v94, 6, v95
	v_and_b32_e32 v9, 32, v9
	v_bitop3_b32 v10, v8, s10, v9 bitop3:0xde
	s_lshl_b32 s10, s11, 5
	s_and_b32 s10, s10, 0x60
	s_add_i32 m0, s9, 0x18000
	v_lshl_add_u64 v[6:7], v[6:7], 0, s[0:1]
	s_mov_b32 s61, s10
	s_lshl_b32 s10, s10, 7
	s_waitcnt vmcnt(2)
	s_barrier
	global_load_lds_dwordx4 v[6:7], off
	v_lshl_add_u64 v[4:5], v[4:5], 0, s[0:1]
	s_add_i32 m0, s9, 0x1a000
	s_add_i32 s97, s9, 0x8000
	v_bitop3_b32 v96, s10, v8, v9 bitop3:0xf6
	global_load_lds_dwordx4 v[4:5], off
	v_lshl_add_u64 v[0:1], v[0:1], 0, s[0:1]
	s_mov_b32 m0, s97
	s_add_i32 s10, s9, 0xa000
	global_load_lds_dwordx4 v[0:1], off
	v_lshl_add_u64 v[0:1], v[2:3], 0, s[0:1]
	s_mov_b32 m0, s10
	s_add_i32 s11, s9, 0x1c000
	global_load_lds_dwordx4 v[0:1], off
	s_add_i32 s14, s9, 0x1e000
	v_lshlrev_b32_e32 v0, 14, v91
	v_and_b32_e32 v0, 0xffff8000, v0
	v_lshl_add_u32 v0, v92, 11, v0
	v_and_b32_e32 v1, 1, v91
	v_lshl_or_b32 v0, v1, 6, v0
	v_lshl_add_u32 v80, v93, 1, v0
	v_lshlrev_b32_e32 v0, 14, v88
	s_cmpk_lt_u32 s15, 0x100
	v_and_b32_e32 v0, 0xffff8000, v0
	s_waitcnt vmcnt(4)
	s_cselect_b64 s[18:19], -1, 0
	v_lshl_add_u32 v0, v89, 11, v0
	v_and_b32_e32 v1, 1, v88
	v_writelane_b32 v239, s18, 62
	s_cmp_lg_u64 s[46:47], 0
	v_lshl_or_b32 v0, v1, 6, v0
	v_writelane_b32 v239, s19, 63
	s_cselect_b64 s[18:19], -1, 0
	v_mov_b32_e32 v81, v165
	v_lshl_add_u32 v82, v90, 1, v0
	v_mov_b32_e32 v83, v165
	s_mov_b32 s15, 0
	v_add_u32_e32 v97, 0, v10
	s_mov_b64 s[50:51], s[4:5]
	s_mov_b64 s[68:69], s[72:73]
	s_barrier
	s_branch .LBB0_111

.LBB0_119:
	s_add_i32 s52, s53, 2
	s_add_u32 s54, s4, 0xfffc0080
	s_addc_u32 s55, s5, -1
	s_add_i32 s56, 0, 0x10000
	v_add_u32_e32 v76, s56, v96
	ds_read_b128 v[32:35], v76
	ds_read_b128 v[36:39], v76 offset:1024
	ds_read_b128 v[72:75], v76 offset:2048
	ds_read_b128 v[76:79], v76 offset:3072
	s_cmp_eq_u32 s76, s53
	s_cselect_b32 s73, s51, s55
	s_cselect_b32 s72, s50, s54
	s_cselect_b32 s55, s69, s91
	s_cselect_b32 s54, s68, s77
	v_lshl_add_u64 v[126:127], s[4:5], 0, v[82:83]
	s_add_i32 m0, s9, 0xc000
	ds_read_b128 v[84:87], v97
	ds_read_b128 v[98:101], v97 offset:1024
	ds_read_b128 v[102:105], v97 offset:2048
	ds_read_b128 v[106:109], v97 offset:3072
	ds_read_b128 v[110:113], v97 offset:4096
	ds_read_b128 v[114:117], v97 offset:5120
	ds_read_b128 v[118:121], v97 offset:6144
	ds_read_b128 v[122:125], v97 offset:7168
	global_load_lds_dwordx4 v[126:127], off
	v_lshl_add_u64 v[126:127], s[4:5], 0, v[80:81]
	s_add_i32 m0, s9, 0xe000
	s_nop 0
	global_load_lds_dwordx4 v[126:127], off
	s_waitcnt vmcnt(6)
	s_waitcnt lgkmcnt(0)
	s_barrier
	s_setprio 1
	s_waitcnt lgkmcnt(0)
	v_mfma_f32_16x16x32_bf16 v[68:71], v[32:35], v[84:87], v[68:71]
	v_mfma_f32_16x16x32_bf16 v[64:67], v[72:75], v[84:87], v[64:67]
	v_mfma_f32_16x16x32_bf16 v[60:63], v[32:35], v[102:105], v[60:63]
	v_mfma_f32_16x16x32_bf16 v[56:59], v[72:75], v[102:105], v[56:59]
	v_mfma_f32_16x16x32_bf16 v[52:55], v[32:35], v[110:113], v[52:55]
	v_mfma_f32_16x16x32_bf16 v[48:51], v[72:75], v[110:113], v[48:51]
	v_mfma_f32_16x16x32_bf16 v[44:47], v[32:35], v[118:121], v[44:47]
	v_mfma_f32_16x16x32_bf16 v[40:43], v[72:75], v[118:121], v[40:43]
	v_mfma_f32_16x16x32_bf16 v[68:71], v[36:39], v[98:101], v[68:71]
	v_mfma_f32_16x16x32_bf16 v[64:67], v[76:79], v[98:101], v[64:67]
	v_mfma_f32_16x16x32_bf16 v[60:63], v[36:39], v[106:109], v[60:63]
	v_mfma_f32_16x16x32_bf16 v[56:59], v[76:79], v[106:109], v[56:59]
	v_mfma_f32_16x16x32_bf16 v[52:55], v[36:39], v[114:117], v[52:55]
	v_mfma_f32_16x16x32_bf16 v[48:51], v[76:79], v[114:117], v[48:51]
	v_mfma_f32_16x16x32_bf16 v[44:47], v[36:39], v[122:125], v[44:47]
	v_mfma_f32_16x16x32_bf16 v[40:43], v[76:79], v[122:125], v[40:43]
	s_setprio 0
	s_barrier
	s_add_i32 s53, s56, s8
	v_lshl_add_u64 v[126:127], s[54:55], 0, v[164:165]
	s_mov_b32 m0, s53
	ds_read_b128 v[84:87], v97 offset:16384
	ds_read_b128 v[98:101], v97 offset:17408
	ds_read_b128 v[102:105], v97 offset:18432
	ds_read_b128 v[106:109], v97 offset:19456
	ds_read_b128 v[110:113], v97 offset:20480
	ds_read_b128 v[114:117], v97 offset:21504
	ds_read_b128 v[118:121], v97 offset:22528
	ds_read_b128 v[122:125], v97 offset:23552
	global_load_lds_dwordx4 v[126:127], off
	v_lshl_add_u64 v[128:129], s[54:55], 0, v[152:153]
	s_add_i32 m0, s53, 0x2000
	v_lshl_add_u64 v[130:131], s[72:73], 0, v[164:165]
	global_load_lds_dwordx4 v[128:129], off
	v_lshl_add_u64 v[132:133], s[72:73], 0, v[152:153]
	s_mov_b32 m0, s9
	s_nop 0
	global_load_lds_dwordx4 v[130:131], off
	s_mov_b32 m0, s13
	s_nop 0
	global_load_lds_dwordx4 v[132:133], off
	s_waitcnt vmcnt(6)
	s_waitcnt lgkmcnt(0)
	s_barrier
	s_setprio 1
	s_waitcnt lgkmcnt(0)
	v_mfma_f32_16x16x32_bf16 v[28:31], v[32:35], v[84:87], v[28:31]
	v_mfma_f32_16x16x32_bf16 v[24:27], v[72:75], v[84:87], v[24:27]
	v_mfma_f32_16x16x32_bf16 v[20:23], v[32:35], v[102:105], v[20:23]
	v_mfma_f32_16x16x32_bf16 v[16:19], v[72:75], v[102:105], v[16:19]
	v_mfma_f32_16x16x32_bf16 v[12:15], v[32:35], v[110:113], v[12:15]
	v_mfma_f32_16x16x32_bf16 v[8:11], v[72:75], v[110:113], v[8:11]
	v_mfma_f32_16x16x32_bf16 v[4:7], v[32:35], v[118:121], v[4:7]
	v_mfma_f32_16x16x32_bf16 v[0:3], v[72:75], v[118:121], v[0:3]
	v_mfma_f32_16x16x32_bf16 v[28:31], v[36:39], v[98:101], v[28:31]
	v_mfma_f32_16x16x32_bf16 v[24:27], v[76:79], v[98:101], v[24:27]
	v_mfma_f32_16x16x32_bf16 v[20:23], v[36:39], v[106:109], v[20:23]
	v_mfma_f32_16x16x32_bf16 v[16:19], v[76:79], v[106:109], v[16:19]
	v_mfma_f32_16x16x32_bf16 v[12:15], v[36:39], v[114:117], v[12:15]
	v_mfma_f32_16x16x32_bf16 v[8:11], v[76:79], v[114:117], v[8:11]
	v_mfma_f32_16x16x32_bf16 v[4:7], v[36:39], v[122:125], v[4:7]
	v_mfma_f32_16x16x32_bf16 v[0:3], v[76:79], v[122:125], v[0:3]
	s_setprio 0
	s_barrier
	s_add_i32 s53, 0, 0x18000
	v_add_u32_e32 v76, s53, v96
	ds_read_b128 v[32:35], v76
	ds_read_b128 v[36:39], v76 offset:1024
	ds_read_b128 v[72:75], v76 offset:2048
	ds_read_b128 v[76:79], v76 offset:3072
	s_add_u32 s54, s72, 0x40000
	s_addc_u32 s55, s73, 0
	s_mov_b32 m0, s89
	v_lshl_add_u64 v[134:135], s[54:55], 0, v[164:165]
	ds_read_b128 v[84:87], v97 offset:32768
	ds_read_b128 v[98:101], v97 offset:33792
	ds_read_b128 v[102:105], v97 offset:34816
	ds_read_b128 v[106:109], v97 offset:35840
	ds_read_b128 v[110:113], v97 offset:36864
	ds_read_b128 v[114:117], v97 offset:37888
	ds_read_b128 v[118:121], v97 offset:38912
	ds_read_b128 v[122:125], v97 offset:39936
	global_load_lds_dwordx4 v[134:135], off
	v_lshl_add_u64 v[134:135], s[54:55], 0, v[152:153]
	s_mov_b32 m0, s3
	s_nop 0
	global_load_lds_dwordx4 v[134:135], off
	s_waitcnt vmcnt(6)
	s_waitcnt lgkmcnt(0)
	s_barrier
	s_setprio 1
	s_waitcnt lgkmcnt(0)
	v_mfma_f32_16x16x32_bf16 v[68:71], v[32:35], v[84:87], v[68:71]
	v_mfma_f32_16x16x32_bf16 v[64:67], v[72:75], v[84:87], v[64:67]
	v_mfma_f32_16x16x32_bf16 v[60:63], v[32:35], v[102:105], v[60:63]
	v_mfma_f32_16x16x32_bf16 v[56:59], v[72:75], v[102:105], v[56:59]
	v_mfma_f32_16x16x32_bf16 v[52:55], v[32:35], v[110:113], v[52:55]
	v_mfma_f32_16x16x32_bf16 v[48:51], v[72:75], v[110:113], v[48:51]
	v_mfma_f32_16x16x32_bf16 v[44:47], v[32:35], v[118:121], v[44:47]
	v_mfma_f32_16x16x32_bf16 v[40:43], v[72:75], v[118:121], v[40:43]
	v_mfma_f32_16x16x32_bf16 v[68:71], v[36:39], v[98:101], v[68:71]
	v_mfma_f32_16x16x32_bf16 v[64:67], v[76:79], v[98:101], v[64:67]
	v_mfma_f32_16x16x32_bf16 v[60:63], v[36:39], v[106:109], v[60:63]
	v_mfma_f32_16x16x32_bf16 v[56:59], v[76:79], v[106:109], v[56:59]
	v_mfma_f32_16x16x32_bf16 v[52:55], v[36:39], v[114:117], v[52:55]
	v_mfma_f32_16x16x32_bf16 v[48:51], v[76:79], v[114:117], v[48:51]
	v_mfma_f32_16x16x32_bf16 v[44:47], v[36:39], v[122:125], v[44:47]
	v_mfma_f32_16x16x32_bf16 v[40:43], v[76:79], v[122:125], v[40:43]
	s_setprio 0
	s_barrier
	s_add_i32 s53, s53, s8
	v_lshl_add_u64 v[126:127], v[126:127], 0, s[0:1]
	s_mov_b32 m0, s53
	ds_read_b128 v[84:87], v97 offset:49152
	ds_read_b128 v[98:101], v97 offset:50176
	ds_read_b128 v[102:105], v97 offset:51200
	ds_read_b128 v[106:109], v97 offset:52224
	ds_read_b128 v[110:113], v97 offset:53248
	ds_read_b128 v[114:117], v97 offset:54272
	ds_read_b128 v[118:121], v97 offset:55296
	ds_read_b128 v[122:125], v97 offset:56320
	global_load_lds_dwordx4 v[126:127], off
	v_lshl_add_u64 v[128:129], v[128:129], 0, s[0:1]
	s_add_i32 m0, s53, 0x2000
	s_nop 0
	global_load_lds_dwordx4 v[128:129], off
	v_lshl_add_u64 v[126:127], v[130:131], 0, s[0:1]
	s_mov_b32 m0, s97
	s_nop 0
	global_load_lds_dwordx4 v[126:127], off
	v_lshl_add_u64 v[126:127], v[132:133], 0, s[0:1]
	s_mov_b32 m0, s10
	s_nop 0
	global_load_lds_dwordx4 v[126:127], off
	s_waitcnt vmcnt(6)
	s_waitcnt lgkmcnt(0)
	s_barrier
	s_setprio 1
	s_waitcnt lgkmcnt(0)
	v_mfma_f32_16x16x32_bf16 v[28:31], v[32:35], v[84:87], v[28:31]
	v_mfma_f32_16x16x32_bf16 v[24:27], v[72:75], v[84:87], v[24:27]
	v_mfma_f32_16x16x32_bf16 v[20:23], v[32:35], v[102:105], v[20:23]
	v_mfma_f32_16x16x32_bf16 v[16:19], v[72:75], v[102:105], v[16:19]
	v_mfma_f32_16x16x32_bf16 v[12:15], v[32:35], v[110:113], v[12:15]
	v_mfma_f32_16x16x32_bf16 v[8:11], v[72:75], v[110:113], v[8:11]
	v_mfma_f32_16x16x32_bf16 v[4:7], v[32:35], v[118:121], v[4:7]
	v_mfma_f32_16x16x32_bf16 v[0:3], v[72:75], v[118:121], v[0:3]
	v_mfma_f32_16x16x32_bf16 v[28:31], v[36:39], v[98:101], v[28:31]
	v_mfma_f32_16x16x32_bf16 v[24:27], v[76:79], v[98:101], v[24:27]
	v_mfma_f32_16x16x32_bf16 v[20:23], v[36:39], v[106:109], v[20:23]
	v_mfma_f32_16x16x32_bf16 v[16:19], v[76:79], v[106:109], v[16:19]
	v_mfma_f32_16x16x32_bf16 v[12:15], v[36:39], v[114:117], v[12:15]
	v_mfma_f32_16x16x32_bf16 v[8:11], v[76:79], v[114:117], v[8:11]
	v_mfma_f32_16x16x32_bf16 v[4:7], v[36:39], v[122:125], v[4:7]
	v_mfma_f32_16x16x32_bf16 v[0:3], v[76:79], v[122:125], v[0:3]
	s_setprio 0
	s_barrier
	s_add_u32 s77, s77, 0x100
	s_addc_u32 s91, s91, 0
	s_add_u32 s4, s4, 0x100
	s_addc_u32 s5, s5, 0
	s_cmp_ge_i32 s52, s47
	s_mov_b32 s53, s52
	s_cbranch_scc0 .LBB0_119
	s_branch .LBB0_121

.LBB0_169:
	v_bfe_i32 v1, v210, 27, 1
	v_lshlrev_b32_e32 v3, 4, v210
	v_lshrrev_b32_e32 v1, 22, v1
	v_ashrrev_i32_e32 v0, 31, v210
	v_add_u32_e32 v1, v3, v1
	v_lshrrev_b32_e32 v0, 26, v0
	v_and_b32_e32 v1, 0xfffffc00, v1
	v_add_u32_e32 v0, v210, v0
	v_sub_u32_e32 v1, v3, v1
	v_ashrrev_i32_e32 v0, 6, v0
	v_lshrrev_b32_e32 v2, 4, v1
	v_bitop3_b32 v2, v2, v1, 32 bitop3:0x6c
	v_lshlrev_b32_e32 v1, 3, v0
	v_and_b32_e32 v4, -16, v1
	v_ashrrev_i32_e32 v1, 31, v2
	v_lshrrev_b32_e32 v1, 26, v1
	v_add_u32_e32 v5, v2, v1
	v_ashrrev_i32_e32 v1, 6, v5
	v_and_b32_e32 v5, 0xc0, v5
	v_sub_u32_e32 v2, v2, v5
	v_lshlrev_b32_e32 v6, 5, v0
	v_ashrrev_i16_sdwa v2, v198, sext(v2) dst_sel:DWORD dst_unused:UNUSED_PAD src0_sel:DWORD src1_sel:BYTE_0
	v_and_b32_e32 v6, 32, v6
	v_bfe_i32 v2, v2, 0, 16
	v_add_u32_e32 v4, v1, v4
	v_and_b32_e32 v8, 3, v1
	s_mov_b32 s7, 0x7ffe0
	v_add_lshl_u32 v6, v6, v2, 1
	v_lshlrev_b32_e32 v5, 1, v4
	v_lshrrev_b32_e32 v7, 2, v4
	v_and_or_b32 v8, v4, s7, v8
	v_lshl_add_u32 v64, v4, 13, v6
	v_add_u32_e32 v4, 0x2000, v3
	v_ashrrev_i32_e32 v3, 31, v4
	v_lshrrev_b32_e32 v3, 22, v3
	v_and_b32_e32 v5, 24, v5
	v_and_b32_e32 v7, 4, v7
	v_add_u32_e32 v3, v4, v3
	v_or3_b32 v5, v8, v7, v5
	v_ashrrev_i32_e32 v3, 10, v3
	v_lshl_add_u32 v164, v5, 13, v6
	v_mul_i32_i24_e32 v5, 0x400, v3
	v_sub_u32_e32 v4, v4, v5
	v_lshrrev_b32_e32 v5, 4, v4
	v_bitop3_b32 v5, v5, v4, 32 bitop3:0x6c
	v_lshlrev_b32_e32 v4, 3, v3
	v_and_b32_e32 v6, -16, v4
	v_ashrrev_i32_e32 v4, 31, v5
	v_lshrrev_b32_e32 v4, 26, v4
	v_add_u32_e32 v7, v5, v4
	v_ashrrev_i32_e32 v4, 6, v7
	v_add_u32_e32 v6, v4, v6
	v_and_b32_e32 v7, 0xc0, v7
	v_and_b32_e32 v10, 3, v4
	v_sub_u32_e32 v5, v5, v7
	v_and_or_b32 v10, v6, s7, v10
	s_ashr_i32 s7, s3, 6
	v_lshlrev_b32_e32 v8, 5, v3
	v_ashrrev_i16_sdwa v5, v198, sext(v5) dst_sel:DWORD dst_unused:UNUSED_PAD src0_sel:DWORD src1_sel:BYTE_0
	v_lshlrev_b32_e32 v7, 1, v6
	v_lshrrev_b32_e32 v9, 2, v6
	s_lshl_b32 s51, s7, 10
	v_and_b32_e32 v8, 32, v8
	v_bfe_i32 v5, v5, 0, 16
	v_and_b32_e32 v7, 24, v7
	v_and_b32_e32 v9, 4, v9
	s_add_i32 s68, s51, 0
	v_or3_b32 v7, v10, v9, v7
	v_add_lshl_u32 v8, v8, v5, 1
	s_add_i32 m0, s68, 0x10000
	v_lshl_add_u32 v68, v7, 13, v8
	global_load_lds_dwordx4 v164, s[42:43]
	s_add_i32 m0, s68, 0x12000
	s_add_i32 s69, s68, 0x14000
	global_load_lds_dwordx4 v68, s[42:43]
	s_add_i32 s71, s68, 0x16000
	s_ashr_i32 s6, s3, 8
	s_add_i32 s72, s68, 0x2000
	s_mov_b32 m0, s68
	s_add_u32 s8, s46, 0x100000
	v_lshl_add_u32 v66, v6, 13, v8
	global_load_lds_dwordx4 v64, s[46:47]
	s_mov_b32 m0, s72
	s_addc_u32 s9, s47, 0
	s_add_i32 s73, s68, 0x4000
	global_load_lds_dwordx4 v66, s[46:47]
	s_mov_b32 m0, s73
	s_add_i32 s76, s68, 0x6000
	global_load_lds_dwordx4 v64, s[8:9]
	s_mov_b32 m0, s76
	s_cmp_eq_u32 s6, 1
	global_load_lds_dwordx4 v66, s[8:9]
	s_cselect_b64 s[82:83], -1, 0
	s_cmp_lg_u32 s6, 1
	s_cbranch_scc1 .LBB0_171
	s_barrier
.LBB0_171:
	v_readlane_b32 s8, v239, 29
	v_lshl_add_u64 v[6:7], s[42:43], 0, v[164:165]
	v_mov_b32_e32 v69, v165
	v_readlane_b32 s9, v239, 30
	s_add_u32 s8, s8, 0x9900000
	v_lshl_add_u64 v[8:9], s[42:43], 0, v[68:69]
	v_mov_b32_e32 v65, v165
	s_addc_u32 s9, s9, 0
	s_add_i32 m0, s68, 0x18000
	v_lshl_add_u64 v[6:7], v[6:7], 0, s[0:1]
	v_lshl_add_u64 v[10:11], s[46:47], 0, v[64:65]
	v_mov_b32_e32 v67, v165
	s_waitcnt vmcnt(2)
	s_barrier
	global_load_lds_dwordx4 v[6:7], off
	v_lshl_add_u64 v[8:9], v[8:9], 0, s[0:1]
	s_add_i32 m0, s68, 0x1a000
	s_add_i32 s89, s68, 0x8000
	v_lshl_add_u64 v[12:13], s[46:47], 0, v[66:67]
	global_load_lds_dwordx4 v[8:9], off
	v_lshl_add_u64 v[10:11], v[10:11], 0, s[0:1]
	s_mov_b32 m0, s89
	s_add_i32 s90, s68, 0xa000
	global_load_lds_dwordx4 v[10:11], off
	v_lshl_add_u64 v[10:11], v[12:13], 0, s[0:1]
	s_mov_b32 m0, s90
	s_add_i32 s91, s68, 0x1c000
	global_load_lds_dwordx4 v[10:11], off
	s_add_i32 s97, s68, 0x1e000
	v_and_b32_e32 v14, 48, v211
	v_lshlrev_b32_e32 v15, 6, v211
	s_movk_i32 s10, 0x3c0
	v_lshlrev_b32_e32 v6, 16, v3
	v_and_or_b32 v14, v15, s10, v14
	v_lshlrev_b32_e32 v15, 2, v211
	v_and_b32_e32 v6, 0xfffe0000, v6
	s_lshl_b32 s77, s6, 6
	s_lshl_b32 s6, s6, 13
	v_and_b32_e32 v15, 32, v15
	v_lshl_add_u32 v4, v4, 13, v6
	v_and_b32_e32 v3, 1, v3
	v_bitop3_b32 v16, v14, s6, v15 bitop3:0xde
	s_lshl_b32 s6, s7, 5
	v_lshl_or_b32 v3, v3, 6, v4
	s_and_b32 s6, s6, 0x60
	v_lshl_add_u32 v70, v5, 1, v3
	v_lshlrev_b32_e32 v3, 16, v0
	s_lshl_b32 s7, s6, 7
	v_and_b32_e32 v3, 0xfffe0000, v3
	s_waitcnt vmcnt(4)
	s_cmpk_lt_u32 s3, 0x100
	v_lshl_add_u32 v1, v1, 13, v3
	v_and_b32_e32 v0, 1, v0
	v_readlane_b32 s12, v240, 62
	s_cselect_b64 s[10:11], -1, 0
	v_lshl_or_b32 v0, v0, 6, v1
	v_readlane_b32 s13, v240, 63
	s_lshl_b32 s12, s6, 1
	v_bitop3_b32 v74, s7, v14, v15 bitop3:0xf6
	v_mov_b32_e32 v71, v165
	v_lshl_add_u32 v72, v2, 1, v0
	v_mov_b32_e32 v73, v165
	s_mov_b32 s3, 0
	v_add_u32_e32 v75, 0, v16
	v_writelane_b32 v240, s12, 62
	s_mov_b64 s[14:15], s[42:43]
	s_mov_b64 s[34:35], s[46:47]
	s_barrier
	v_writelane_b32 v240, s13, 63
	s_branch .LBB0_174

.LBB0_181:
	s_add_i32 s52, s46, 2
	s_add_u32 s53, s42, 0xfff00080
	s_addc_u32 s47, s43, -1
	s_add_i32 s56, 0, 0x10000
	v_add_u32_e32 v88, s56, v74
	ds_read_b128 v[76:79], v88
	ds_read_b128 v[80:83], v88 offset:1024
	ds_read_b128 v[84:87], v88 offset:2048
	ds_read_b128 v[88:91], v88 offset:3072
	s_cmp_eq_u32 s7, s46
	s_cselect_b32 s46, s34, s53
	s_cselect_b32 s47, s35, s47
	s_cselect_b32 s55, s15, vcc_hi
	s_cselect_b32 s54, s14, vcc_lo
	v_lshl_add_u64 v[124:125], s[42:43], 0, v[72:73]
	s_add_i32 m0, s68, 0xc000
	ds_read_b128 v[92:95], v75
	ds_read_b128 v[96:99], v75 offset:1024
	ds_read_b128 v[100:103], v75 offset:2048
	ds_read_b128 v[104:107], v75 offset:3072
	ds_read_b128 v[108:111], v75 offset:4096
	ds_read_b128 v[112:115], v75 offset:5120
	ds_read_b128 v[116:119], v75 offset:6144
	ds_read_b128 v[120:123], v75 offset:7168
	global_load_lds_dwordx4 v[124:125], off
	v_lshl_add_u64 v[124:125], s[42:43], 0, v[70:71]
	s_add_i32 m0, s68, 0xe000
	s_nop 0
	global_load_lds_dwordx4 v[124:125], off
	s_waitcnt vmcnt(6)
	s_waitcnt lgkmcnt(0)
	s_barrier
	s_setprio 1
	s_waitcnt lgkmcnt(0)
	v_mfma_f32_16x16x32_bf16 v[60:63], v[76:79], v[92:95], v[60:63]
	v_mfma_f32_16x16x32_bf16 v[56:59], v[84:87], v[92:95], v[56:59]
	v_mfma_f32_16x16x32_bf16 v[52:55], v[76:79], v[100:103], v[52:55]
	v_mfma_f32_16x16x32_bf16 v[48:51], v[84:87], v[100:103], v[48:51]
	v_mfma_f32_16x16x32_bf16 v[44:47], v[76:79], v[108:111], v[44:47]
	v_mfma_f32_16x16x32_bf16 v[40:43], v[84:87], v[108:111], v[40:43]
	v_mfma_f32_16x16x32_bf16 v[36:39], v[76:79], v[116:119], v[36:39]
	v_mfma_f32_16x16x32_bf16 v[32:35], v[84:87], v[116:119], v[32:35]
	v_mfma_f32_16x16x32_bf16 v[60:63], v[80:83], v[96:99], v[60:63]
	v_mfma_f32_16x16x32_bf16 v[56:59], v[88:91], v[96:99], v[56:59]
	v_mfma_f32_16x16x32_bf16 v[52:55], v[80:83], v[104:107], v[52:55]
	v_mfma_f32_16x16x32_bf16 v[48:51], v[88:91], v[104:107], v[48:51]
	v_mfma_f32_16x16x32_bf16 v[44:47], v[80:83], v[112:115], v[44:47]
	v_mfma_f32_16x16x32_bf16 v[40:43], v[88:91], v[112:115], v[40:43]
	v_mfma_f32_16x16x32_bf16 v[36:39], v[80:83], v[120:123], v[36:39]
	v_mfma_f32_16x16x32_bf16 v[32:35], v[88:91], v[120:123], v[32:35]
	s_setprio 0
	s_barrier
	s_add_i32 s53, s56, s51
	v_lshl_add_u64 v[124:125], s[54:55], 0, v[164:165]
	s_mov_b32 m0, s53
	ds_read_b128 v[92:95], v75 offset:16384
	ds_read_b128 v[96:99], v75 offset:17408
	ds_read_b128 v[100:103], v75 offset:18432
	ds_read_b128 v[104:107], v75 offset:19456
	ds_read_b128 v[108:111], v75 offset:20480
	ds_read_b128 v[112:115], v75 offset:21504
	ds_read_b128 v[116:119], v75 offset:22528
	ds_read_b128 v[120:123], v75 offset:23552
	global_load_lds_dwordx4 v[124:125], off
	v_lshl_add_u64 v[126:127], s[54:55], 0, v[68:69]
	s_add_i32 m0, s53, 0x2000
	v_lshl_add_u64 v[128:129], s[46:47], 0, v[64:65]
	global_load_lds_dwordx4 v[126:127], off
	v_lshl_add_u64 v[130:131], s[46:47], 0, v[66:67]
	s_mov_b32 m0, s68
	s_nop 0
	global_load_lds_dwordx4 v[128:129], off
	s_mov_b32 m0, s72
	s_nop 0
	global_load_lds_dwordx4 v[130:131], off
	s_waitcnt vmcnt(6)
	s_waitcnt lgkmcnt(0)
	s_barrier
	s_setprio 1
	s_waitcnt lgkmcnt(0)
	v_mfma_f32_16x16x32_bf16 v[28:31], v[76:79], v[92:95], v[28:31]
	v_mfma_f32_16x16x32_bf16 v[24:27], v[84:87], v[92:95], v[24:27]
	v_mfma_f32_16x16x32_bf16 v[20:23], v[76:79], v[100:103], v[20:23]
	v_mfma_f32_16x16x32_bf16 v[16:19], v[84:87], v[100:103], v[16:19]
	v_mfma_f32_16x16x32_bf16 v[12:15], v[76:79], v[108:111], v[12:15]
	v_mfma_f32_16x16x32_bf16 v[8:11], v[84:87], v[108:111], v[8:11]
	v_mfma_f32_16x16x32_bf16 v[4:7], v[76:79], v[116:119], v[4:7]
	v_mfma_f32_16x16x32_bf16 v[0:3], v[84:87], v[116:119], v[0:3]
	v_mfma_f32_16x16x32_bf16 v[28:31], v[80:83], v[96:99], v[28:31]
	v_mfma_f32_16x16x32_bf16 v[24:27], v[88:91], v[96:99], v[24:27]
	v_mfma_f32_16x16x32_bf16 v[20:23], v[80:83], v[104:107], v[20:23]
	v_mfma_f32_16x16x32_bf16 v[16:19], v[88:91], v[104:107], v[16:19]
	v_mfma_f32_16x16x32_bf16 v[12:15], v[80:83], v[112:115], v[12:15]
	v_mfma_f32_16x16x32_bf16 v[8:11], v[88:91], v[112:115], v[8:11]
	v_mfma_f32_16x16x32_bf16 v[4:7], v[80:83], v[120:123], v[4:7]
	v_mfma_f32_16x16x32_bf16 v[0:3], v[88:91], v[120:123], v[0:3]
	s_setprio 0
	s_barrier
	s_add_i32 s53, 0, 0x18000
	v_add_u32_e32 v88, s53, v74
	ds_read_b128 v[76:79], v88
	ds_read_b128 v[80:83], v88 offset:1024
	ds_read_b128 v[84:87], v88 offset:2048
	ds_read_b128 v[88:91], v88 offset:3072
	s_add_u32 s46, s46, 0x100000
	s_addc_u32 s47, s47, 0
	s_mov_b32 m0, s73
	v_lshl_add_u64 v[132:133], s[46:47], 0, v[64:65]
	ds_read_b128 v[92:95], v75 offset:32768
	ds_read_b128 v[96:99], v75 offset:33792
	ds_read_b128 v[100:103], v75 offset:34816
	ds_read_b128 v[104:107], v75 offset:35840
	ds_read_b128 v[108:111], v75 offset:36864
	ds_read_b128 v[112:115], v75 offset:37888
	ds_read_b128 v[116:119], v75 offset:38912
	ds_read_b128 v[120:123], v75 offset:39936
	global_load_lds_dwordx4 v[132:133], off
	v_lshl_add_u64 v[132:133], s[46:47], 0, v[66:67]
	s_mov_b32 m0, s76
	s_nop 0
	global_load_lds_dwordx4 v[132:133], off
	s_waitcnt vmcnt(6)
	s_waitcnt lgkmcnt(0)
	s_barrier
	s_setprio 1
	s_waitcnt lgkmcnt(0)
	v_mfma_f32_16x16x32_bf16 v[60:63], v[76:79], v[92:95], v[60:63]
	v_mfma_f32_16x16x32_bf16 v[56:59], v[84:87], v[92:95], v[56:59]
	v_mfma_f32_16x16x32_bf16 v[52:55], v[76:79], v[100:103], v[52:55]
	v_mfma_f32_16x16x32_bf16 v[48:51], v[84:87], v[100:103], v[48:51]
	v_mfma_f32_16x16x32_bf16 v[44:47], v[76:79], v[108:111], v[44:47]
	v_mfma_f32_16x16x32_bf16 v[40:43], v[84:87], v[108:111], v[40:43]
	v_mfma_f32_16x16x32_bf16 v[36:39], v[76:79], v[116:119], v[36:39]
	v_mfma_f32_16x16x32_bf16 v[32:35], v[84:87], v[116:119], v[32:35]
	v_mfma_f32_16x16x32_bf16 v[60:63], v[80:83], v[96:99], v[60:63]
	v_mfma_f32_16x16x32_bf16 v[56:59], v[88:91], v[96:99], v[56:59]
	v_mfma_f32_16x16x32_bf16 v[52:55], v[80:83], v[104:107], v[52:55]
	v_mfma_f32_16x16x32_bf16 v[48:51], v[88:91], v[104:107], v[48:51]
	v_mfma_f32_16x16x32_bf16 v[44:47], v[80:83], v[112:115], v[44:47]
	v_mfma_f32_16x16x32_bf16 v[40:43], v[88:91], v[112:115], v[40:43]
	v_mfma_f32_16x16x32_bf16 v[36:39], v[80:83], v[120:123], v[36:39]
	v_mfma_f32_16x16x32_bf16 v[32:35], v[88:91], v[120:123], v[32:35]
	s_setprio 0
	s_barrier
	s_add_i32 s46, s53, s51
	v_lshl_add_u64 v[124:125], v[124:125], 0, s[0:1]
	s_mov_b32 m0, s46
	ds_read_b128 v[92:95], v75 offset:49152
	ds_read_b128 v[96:99], v75 offset:50176
	ds_read_b128 v[100:103], v75 offset:51200
	ds_read_b128 v[104:107], v75 offset:52224
	ds_read_b128 v[108:111], v75 offset:53248
	ds_read_b128 v[112:115], v75 offset:54272
	ds_read_b128 v[116:119], v75 offset:55296
	ds_read_b128 v[120:123], v75 offset:56320
	global_load_lds_dwordx4 v[124:125], off
	v_lshl_add_u64 v[126:127], v[126:127], 0, s[0:1]
	s_add_i32 m0, s46, 0x2000
	s_nop 0
	global_load_lds_dwordx4 v[126:127], off
	v_lshl_add_u64 v[124:125], v[128:129], 0, s[0:1]
	s_mov_b32 m0, s89
	s_nop 0
	global_load_lds_dwordx4 v[124:125], off
	v_lshl_add_u64 v[124:125], v[130:131], 0, s[0:1]
	s_mov_b32 m0, s90
	s_nop 0
	global_load_lds_dwordx4 v[124:125], off
	s_waitcnt vmcnt(6)
	s_waitcnt lgkmcnt(0)
	s_barrier
	s_setprio 1
	s_waitcnt lgkmcnt(0)
	v_mfma_f32_16x16x32_bf16 v[28:31], v[76:79], v[92:95], v[28:31]
	v_mfma_f32_16x16x32_bf16 v[24:27], v[84:87], v[92:95], v[24:27]
	v_mfma_f32_16x16x32_bf16 v[20:23], v[76:79], v[100:103], v[20:23]
	v_mfma_f32_16x16x32_bf16 v[16:19], v[84:87], v[100:103], v[16:19]
	v_mfma_f32_16x16x32_bf16 v[12:15], v[76:79], v[108:111], v[12:15]
	v_mfma_f32_16x16x32_bf16 v[8:11], v[84:87], v[108:111], v[8:11]
	v_mfma_f32_16x16x32_bf16 v[4:7], v[76:79], v[116:119], v[4:7]
	v_mfma_f32_16x16x32_bf16 v[0:3], v[84:87], v[116:119], v[0:3]
	v_mfma_f32_16x16x32_bf16 v[28:31], v[80:83], v[96:99], v[28:31]
	v_mfma_f32_16x16x32_bf16 v[24:27], v[88:91], v[96:99], v[24:27]
	v_mfma_f32_16x16x32_bf16 v[20:23], v[80:83], v[104:107], v[20:23]
	v_mfma_f32_16x16x32_bf16 v[16:19], v[88:91], v[104:107], v[16:19]
	v_mfma_f32_16x16x32_bf16 v[12:15], v[80:83], v[112:115], v[12:15]
	v_mfma_f32_16x16x32_bf16 v[8:11], v[88:91], v[112:115], v[8:11]
	v_mfma_f32_16x16x32_bf16 v[4:7], v[80:83], v[120:123], v[4:7]
	v_mfma_f32_16x16x32_bf16 v[0:3], v[88:91], v[120:123], v[0:3]
	s_setprio 0
	s_barrier
	s_add_u32 vcc_lo, vcc_lo, 0x100
	s_addc_u32 vcc_hi, vcc_hi, 0
	s_add_u32 s42, s42, 0x100
	s_addc_u32 s43, s43, 0
	s_cmp_ge_i32 s52, s33
	s_mov_b32 s46, s52
	s_cbranch_scc0 .LBB0_181
	s_and_b64 vcc, exec, s[10:11]
	s_cbranch_vccz .LBB0_184

.LBB0_194:
	s_ashr_i32 s9, s8, 3
	s_and_b32 s4, s8, 7
	s_waitcnt vmcnt(0) lgkmcnt(0)
	s_barrier
	s_and_saveexec_b64 s[14:15], s[12:13]
	s_movk_i32 s5, 0x110
	s_movk_i32 s33, 0xdff
	s_cbranch_execz .LBB0_197
	s_lshl_b32 s38, s4, 8
	s_mov_b32 s39, 0
	s_lshl_b32 s3, s9, 8
	v_lshl_add_u64 v[0:1], v[172:173], 0, s[38:39]
	v_ashrrev_i32_e32 v3, 4, v210
	v_add_u32_e32 v4, s3, v3
	v_ashrrev_i32_e32 v5, 31, v4
	v_lshlrev_b64 v[4:5], 11, v[4:5]
	v_lshl_add_u64 v[4:5], v[0:1], 0, v[4:5]
	s_mov_b64 s[34:35], 0x10000
	v_mad_u64_u32 v[8:9], vcc, v3, s5, v[174:175]
	global_load_dwordx4 v[100:103], v[4:5], off
	v_lshl_add_u64 v[4:5], v[4:5], 0, s[34:35]
	global_load_dwordx4 v[104:107], v[4:5], off
	v_lshl_add_u64 v[4:5], v[4:5], 0, s[34:35]
	global_load_dwordx4 v[108:111], v[4:5], off
	v_lshl_add_u64 v[4:5], v[4:5], 0, s[34:35]
	global_load_dwordx4 v[112:115], v[4:5], off
	v_lshl_add_u64 v[4:5], v[4:5], 0, s[34:35]
	global_load_dwordx4 v[116:119], v[4:5], off
	v_lshl_add_u64 v[4:5], v[4:5], 0, s[34:35]
	global_load_dwordx4 v[120:123], v[4:5], off
	v_lshl_add_u64 v[4:5], v[4:5], 0, s[34:35]
	global_load_dwordx4 v[124:127], v[4:5], off
	v_lshl_add_u64 v[4:5], v[4:5], 0, s[34:35]
	global_load_dwordx4 v[128:131], v[4:5], off
	s_waitcnt vmcnt(7)
	ds_write_b128 v8, v[100:103]
	s_waitcnt vmcnt(6)
	ds_write_b128 v8, v[104:107] offset:8704
	s_waitcnt vmcnt(5)
	ds_write_b128 v8, v[108:111] offset:17408
	s_waitcnt vmcnt(4)
	ds_write_b128 v8, v[112:115] offset:26112
	s_waitcnt vmcnt(3)
	ds_write_b128 v8, v[116:119] offset:34816
	s_waitcnt vmcnt(2)
	ds_write_b128 v8, v[120:123] offset:43520
	s_waitcnt vmcnt(1)
	ds_write_b128 v8, v[124:127] offset:52224
	s_waitcnt vmcnt(0)
	ds_write_b128 v8, v[128:131] offset:60928

.LBB0_255:
	s_ashr_i32 s14, s13, 3
	s_and_b32 s15, s13, 7
	s_waitcnt vmcnt(0) lgkmcnt(0)
	s_barrier
	s_and_saveexec_b64 s[8:9], s[4:5]
	s_movk_i32 s19, 0x110
	s_movk_i32 s33, 0xdff
	s_cbranch_execz .LBB0_258
	s_lshl_b32 s34, s15, 8
	s_mov_b32 s35, 0
	s_lshl_b32 s18, s14, 8
	v_lshl_add_u64 v[0:1], v[116:117], 0, s[34:35]
	v_ashrrev_i32_e32 v3, 4, v210
	v_add_u32_e32 v4, s18, v3
	v_ashrrev_i32_e32 v5, 31, v4
	v_lshlrev_b64 v[4:5], 11, v[4:5]
	v_lshl_add_u64 v[4:5], v[0:1], 0, v[4:5]
	s_mov_b64 s[10:11], 0x10000
	v_mad_u64_u32 v[8:9], vcc, v3, s19, v[118:119]
	global_load_dwordx4 v[80:83], v[4:5], off
	v_lshl_add_u64 v[4:5], v[4:5], 0, s[10:11]
	global_load_dwordx4 v[84:87], v[4:5], off
	v_lshl_add_u64 v[4:5], v[4:5], 0, s[10:11]
	global_load_dwordx4 v[88:91], v[4:5], off
	v_lshl_add_u64 v[4:5], v[4:5], 0, s[10:11]
	global_load_dwordx4 v[92:95], v[4:5], off
	v_lshl_add_u64 v[4:5], v[4:5], 0, s[10:11]
	global_load_dwordx4 v[96:99], v[4:5], off
	v_lshl_add_u64 v[4:5], v[4:5], 0, s[10:11]
	global_load_dwordx4 v[100:103], v[4:5], off
	v_lshl_add_u64 v[4:5], v[4:5], 0, s[10:11]
	global_load_dwordx4 v[104:107], v[4:5], off
	v_lshl_add_u64 v[4:5], v[4:5], 0, s[10:11]
	global_load_dwordx4 v[108:111], v[4:5], off
	s_waitcnt vmcnt(7)
	ds_write_b128 v8, v[80:83]
	s_waitcnt vmcnt(6)
	ds_write_b128 v8, v[84:87] offset:8704
	s_waitcnt vmcnt(5)
	ds_write_b128 v8, v[88:91] offset:17408
	s_waitcnt vmcnt(4)
	ds_write_b128 v8, v[92:95] offset:26112
	s_waitcnt vmcnt(3)
	ds_write_b128 v8, v[96:99] offset:34816
	s_waitcnt vmcnt(2)
	ds_write_b128 v8, v[100:103] offset:43520
	s_waitcnt vmcnt(1)
	ds_write_b128 v8, v[104:107] offset:52224
	s_waitcnt vmcnt(0)
	ds_write_b128 v8, v[108:111] offset:60928

.LBB0_271:
	v_ashrrev_i32_e32 v1, 31, v210
	v_lshrrev_b32_e32 v1, 26, v1
	v_add_u32_e32 v1, v210, v1
	v_ashrrev_i32_e32 v8, 6, v1
	v_bfe_i32 v1, v210, 27, 1
	v_lshlrev_b32_e32 v0, 4, v210
	v_lshrrev_b32_e32 v1, 22, v1
	v_add_u32_e32 v1, v0, v1
	v_and_b32_e32 v1, 0xfffffc00, v1
	v_sub_u32_e32 v1, v0, v1
	v_lshrrev_b32_e32 v2, 4, v1
	v_bitop3_b32 v1, v2, v1, 32 bitop3:0x6c
	s_add_u32 s3, s10, 0x10100000
	v_ashrrev_i32_e32 v3, 31, v1
	s_waitcnt lgkmcnt(0)
	s_addc_u32 s42, s11, 0
	s_mul_i32 s7, s79, 0x580000
	v_lshrrev_b32_e32 v3, 26, v3
	s_mul_hi_i32 s5, s79, 0x580000
	s_add_u32 s7, s10, s7
	v_add_u32_e32 v3, v1, v3
	s_addc_u32 s5, s11, s5
	v_lshlrev_b32_e32 v2, 3, v8
	v_ashrrev_i32_e32 v10, 6, v3
	v_and_b32_e32 v3, 0xc0, v3
	s_add_u32 s43, s7, 0x5300000
	v_and_b32_e32 v2, 0xfffff0, v2
	v_sub_u32_e32 v1, v1, v3
	s_addc_u32 s46, s5, 0
	v_add_u32_e32 v2, v10, v2
	v_lshlrev_b32_e32 v4, 5, v8
	v_ashrrev_i16_sdwa v1, v198, sext(v1) dst_sel:DWORD dst_unused:UNUSED_PAD src0_sel:DWORD src1_sel:BYTE_0
	s_movk_i32 s5, 0xb00
	v_and_b32_e32 v9, 32, v4
	v_bfe_i32 v11, v1, 0, 16
	v_mul_lo_u32 v1, v2, s5
	v_or_b32_e32 v1, v1, v9
	v_add_u32_e32 v0, 0x2000, v0
	v_add_lshl_u32 v164, v1, v11, 1
	v_ashrrev_i32_e32 v1, 31, v0
	v_lshrrev_b32_e32 v1, 22, v1
	v_add_u32_e32 v1, v0, v1
	v_ashrrev_i32_e32 v12, 10, v1
	v_mul_i32_i24_e32 v1, 0x400, v12
	v_sub_u32_e32 v0, v0, v1
	v_lshrrev_b32_e32 v1, 4, v0
	v_bitop3_b32 v0, v1, v0, 32 bitop3:0x6c
	v_ashrrev_i32_e32 v2, 31, v0
	v_lshrrev_b32_e32 v2, 26, v2
	v_add_u32_e32 v2, v0, v2
	v_lshlrev_b32_e32 v1, 3, v12
	v_ashrrev_i32_e32 v14, 6, v2
	v_and_b32_e32 v2, 0xc0, v2
	v_and_b32_e32 v1, 0xfffff0, v1
	v_sub_u32_e32 v0, v0, v2
	v_add_u32_e32 v1, v14, v1
	v_ashrrev_i16_sdwa v0, v198, sext(v0) dst_sel:DWORD dst_unused:UNUSED_PAD src0_sel:DWORD src1_sel:BYTE_0
	s_add_i32 s4, s6, s4
	v_bfe_i32 v15, v0, 0, 16
	v_mul_lo_u32 v0, v1, s5
	s_ashr_i32 s5, s4, 31
	s_lshr_b32 s5, s5, 24
	s_add_i32 s5, s4, s5
	s_ashr_i32 s6, s5, 8
	s_and_b32 s5, s5, 0xffffff00
	s_sub_i32 s4, s4, s5
	s_sext_i32_i16 s5, s4
	s_bfe_u32 s5, s5, 0x60019
	s_add_i32 s5, s4, s5
	s_sub_i32 s7, 0, s6
	s_sext_i32_i16 s6, s5
	s_and_b32 s5, s5, 0xffc0
	s_sub_i32 s4, s4, s5
	s_bfe_i32 s5, s4, 0x80000
	s_bfe_u32 s5, s5, 0x3000c
	s_ashr_i32 s6, s6, 6
	s_add_i32 s5, s4, s5
	s_lshl_b32 s11, s6, 3
	s_bfe_i32 s6, s5, 0x80000
	s_and_b32 s5, s5, 0xf8
	s_sub_i32 s4, s4, s5
	s_sext_i32_i8 s4, s4
	s_add_i32 s33, s11, s4
	s_ashr_i32 s10, s8, 6
	s_sext_i32_i16 s12, s6
	s_mul_i32 s5, s33, 0x160000
	s_ashr_i32 s9, s8, 8
	s_lshl_b32 s47, s10, 10
	s_lshr_b32 s6, s12, 3
	s_mul_hi_u32 s4, s7, 0x1600
	s_mulk_i32 s7, 0x1600
	s_ashr_i32 s11, s5, 31
	s_add_u32 s13, s3, s7
	s_addc_u32 s14, s42, s4
	s_add_u32 s18, s13, s5
	s_addc_u32 s19, s14, s11
	s_ashr_i32 s5, s12, 3
	s_add_u32 s7, s43, s7
	s_mul_hi_i32 s11, s5, 0xb0000
	s_mul_i32 s5, s5, 0xb0000
	s_addc_u32 s4, s46, s4
	v_lshlrev_b32_e32 v3, 5, v12
	s_add_u32 s34, s7, s5
	v_and_b32_e32 v13, 32, v3
	s_addc_u32 s35, s4, s11
	s_add_i32 s50, s47, 0
	v_or_b32_e32 v0, v0, v13
	s_add_i32 m0, s50, 0x10000
	v_add_lshl_u32 v64, v0, v15, 1
	global_load_lds_dwordx4 v164, s[34:35]
	s_add_i32 m0, s50, 0x12000
	s_add_i32 s51, s50, 0x14000
	global_load_lds_dwordx4 v64, s[34:35]
	s_add_i32 s56, s50, 0x16000
	s_add_i32 s57, s50, 0x2000
	s_mov_b32 m0, s50
	s_add_u32 s4, s18, 0xb0000
	global_load_lds_dwordx4 v164, s[18:19]
	s_mov_b32 m0, s57
	s_addc_u32 s5, s19, 0
	s_add_i32 s58, s50, 0x4000
	global_load_lds_dwordx4 v64, s[18:19]
	s_mov_b32 m0, s58
	s_add_i32 s59, s50, 0x6000
	global_load_lds_dwordx4 v164, s[4:5]
	s_mov_b32 m0, s59
	v_mov_b32_e32 v65, v165
	global_load_lds_dwordx4 v64, s[4:5]
	s_cmp_eq_u32 s9, 1
	v_lshl_add_u64 v[6:7], s[34:35], 0, v[164:165]
	v_lshl_add_u64 v[4:5], s[34:35], 0, v[64:65]
	v_lshl_add_u64 v[0:1], s[18:19], 0, v[164:165]
	s_cselect_b64 s[4:5], -1, 0
	s_cmp_lg_u32 s9, 1
	v_lshl_add_u64 v[2:3], s[18:19], 0, v[64:65]
	s_cbranch_scc1 .LBB0_273
	s_barrier
.LBB0_273:
	s_sext_i32_i8 s77, s6
	v_readlane_b32 s6, v239, 29
	v_readlane_b32 s7, v239, 30
	s_add_u32 s6, s6, 0x6900000
	s_addc_u32 s7, s7, 0
	v_readlane_b32 s12, v239, 51
	v_readlane_b32 s13, v239, 52
	s_add_u32 s68, s12, 0x5000
	s_addc_u32 s69, s13, 0
	s_add_i32 m0, s50, 0x18000
	v_lshl_add_u64 v[6:7], v[6:7], 0, s[0:1]
	s_waitcnt vmcnt(2)
	s_barrier
	global_load_lds_dwordx4 v[6:7], off
	v_lshl_add_u64 v[4:5], v[4:5], 0, s[0:1]
	s_add_i32 m0, s50, 0x1a000
	s_add_i32 s72, s50, 0x8000
	global_load_lds_dwordx4 v[4:5], off
	v_lshl_add_u64 v[0:1], v[0:1], 0, s[0:1]
	s_mov_b32 m0, s72
	s_add_i32 s73, s50, 0xa000
	global_load_lds_dwordx4 v[0:1], off
	v_lshl_add_u64 v[0:1], v[2:3], 0, s[0:1]
	s_mov_b32 m0, s73
	s_add_i32 s89, s50, 0x1c000
	global_load_lds_dwordx4 v[0:1], off
	s_add_i32 s90, s50, 0x1e000
	v_and_b32_e32 v16, 48, v211
	v_lshlrev_b32_e32 v17, 6, v211
	s_movk_i32 s11, 0x3c0
	v_and_or_b32 v16, v17, s11, v16
	v_lshlrev_b32_e32 v17, 2, v211
	s_movk_i32 s12, 0xb00
	s_lshl_b32 s70, s9, 6
	s_lshl_b32 s9, s9, 13
	v_and_b32_e32 v17, 32, v17
	v_lshrrev_b32_e32 v1, 1, v12
	v_mul_lo_u32 v0, v14, s12
	s_mov_b32 s13, 0xb000
	v_bitop3_b32 v18, v16, s9, v17 bitop3:0xde
	s_lshl_b32 s9, s10, 5
	v_mad_u64_u32 v[0:1], s[10:11], v1, s13, v[0:1]
	v_or_b32_e32 v0, v0, v13
	v_add_lshl_u32 v0, v0, v15, 1
	v_mov_b32_e32 v1, v165
	s_mov_b64 s[14:15], 0xb0080
	v_lshl_add_u64 v[66:67], v[0:1], 0, s[14:15]
	v_lshrrev_b32_e32 v1, 1, v8
	v_mul_lo_u32 v0, v10, s12
	s_and_b32 s71, s9, 0x60
	v_mad_u64_u32 v[0:1], s[10:11], v1, s13, v[0:1]
	s_lshl_b32 s9, s71, 7
	s_waitcnt vmcnt(4)
	v_or_b32_e32 v0, v0, v9
	s_cmpk_lt_u32 s8, 0x100
	v_add_lshl_u32 v0, v0, v11, 1
	v_mov_b32_e32 v1, v165
	v_bitop3_b32 v82, s9, v16, v17 bitop3:0xf6
	s_cselect_b64 s[8:9], -1, 0
	v_lshl_add_u64 v[68:69], v[0:1], 0, s[14:15]
	s_mov_b32 s91, 0
	v_add_u32_e32 v83, 0, v18
	s_mov_b64 s[12:13], s[18:19]
	s_mov_b64 s[14:15], s[34:35]
	s_barrier
	s_branch .LBB0_276

.LBB0_284:
	s_add_i32 s54, s38, 2
	s_add_u32 s34, s18, 0x100
	s_addc_u32 s35, s19, 0
	s_add_i32 s55, 0, 0x10000
	v_add_u32_e32 v84, s55, v82
	ds_read_b128 v[70:73], v84
	ds_read_b128 v[74:77], v84 offset:1024
	ds_read_b128 v[78:81], v84 offset:2048
	ds_read_b128 v[84:87], v84 offset:3072
	s_cmp_eq_u32 vcc_hi, s38
	s_cselect_b32 s38, s12, s34
	s_cselect_b32 s39, s13, s35
	s_cselect_b32 s61, s15, s53
	s_cselect_b32 s60, s14, s52
	v_lshl_add_u64 v[120:121], s[18:19], 0, v[68:69]
	s_add_i32 m0, s50, 0xc000
	ds_read_b128 v[88:91], v83
	ds_read_b128 v[92:95], v83 offset:1024
	ds_read_b128 v[96:99], v83 offset:2048
	ds_read_b128 v[100:103], v83 offset:3072
	ds_read_b128 v[104:107], v83 offset:4096
	ds_read_b128 v[108:111], v83 offset:5120
	ds_read_b128 v[112:115], v83 offset:6144
	ds_read_b128 v[116:119], v83 offset:7168
	global_load_lds_dwordx4 v[120:121], off
	v_lshl_add_u64 v[120:121], s[18:19], 0, v[66:67]
	s_add_i32 m0, s50, 0xe000
	s_nop 0
	global_load_lds_dwordx4 v[120:121], off
	s_waitcnt vmcnt(6)
	s_waitcnt lgkmcnt(0)
	s_barrier
	s_setprio 1
	s_waitcnt lgkmcnt(0)
	v_mfma_f32_16x16x32_bf16 v[60:63], v[70:73], v[88:91], v[60:63]
	v_mfma_f32_16x16x32_bf16 v[56:59], v[78:81], v[88:91], v[56:59]
	v_mfma_f32_16x16x32_bf16 v[52:55], v[70:73], v[96:99], v[52:55]
	v_mfma_f32_16x16x32_bf16 v[48:51], v[78:81], v[96:99], v[48:51]
	v_mfma_f32_16x16x32_bf16 v[44:47], v[70:73], v[104:107], v[44:47]
	v_mfma_f32_16x16x32_bf16 v[40:43], v[78:81], v[104:107], v[40:43]
	v_mfma_f32_16x16x32_bf16 v[36:39], v[70:73], v[112:115], v[36:39]
	v_mfma_f32_16x16x32_bf16 v[32:35], v[78:81], v[112:115], v[32:35]
	v_mfma_f32_16x16x32_bf16 v[60:63], v[74:77], v[92:95], v[60:63]
	v_mfma_f32_16x16x32_bf16 v[56:59], v[84:87], v[92:95], v[56:59]
	v_mfma_f32_16x16x32_bf16 v[52:55], v[74:77], v[100:103], v[52:55]
	v_mfma_f32_16x16x32_bf16 v[48:51], v[84:87], v[100:103], v[48:51]
	v_mfma_f32_16x16x32_bf16 v[44:47], v[74:77], v[108:111], v[44:47]
	v_mfma_f32_16x16x32_bf16 v[40:43], v[84:87], v[108:111], v[40:43]
	v_mfma_f32_16x16x32_bf16 v[36:39], v[74:77], v[116:119], v[36:39]
	v_mfma_f32_16x16x32_bf16 v[32:35], v[84:87], v[116:119], v[32:35]
	s_setprio 0
	s_barrier
	s_add_i32 s18, s55, s47
	v_lshl_add_u64 v[120:121], s[60:61], 0, v[164:165]
	s_mov_b32 m0, s18
	ds_read_b128 v[88:91], v83 offset:16384
	ds_read_b128 v[92:95], v83 offset:17408
	ds_read_b128 v[96:99], v83 offset:18432
	ds_read_b128 v[100:103], v83 offset:19456
	ds_read_b128 v[104:107], v83 offset:20480
	ds_read_b128 v[108:111], v83 offset:21504
	ds_read_b128 v[112:115], v83 offset:22528
	ds_read_b128 v[116:119], v83 offset:23552
	global_load_lds_dwordx4 v[120:121], off
	v_lshl_add_u64 v[122:123], s[60:61], 0, v[64:65]
	s_add_i32 m0, s18, 0x2000
	v_lshl_add_u64 v[124:125], s[38:39], 0, v[164:165]
	global_load_lds_dwordx4 v[122:123], off
	v_lshl_add_u64 v[126:127], s[38:39], 0, v[64:65]
	s_mov_b32 m0, s50
	s_nop 0
	global_load_lds_dwordx4 v[124:125], off
	s_mov_b32 m0, s57
	s_nop 0
	global_load_lds_dwordx4 v[126:127], off
	s_waitcnt vmcnt(6)
	s_waitcnt lgkmcnt(0)
	s_barrier
	s_setprio 1
	s_waitcnt lgkmcnt(0)
	v_mfma_f32_16x16x32_bf16 v[28:31], v[70:73], v[88:91], v[28:31]
	v_mfma_f32_16x16x32_bf16 v[24:27], v[78:81], v[88:91], v[24:27]
	v_mfma_f32_16x16x32_bf16 v[20:23], v[70:73], v[96:99], v[20:23]
	v_mfma_f32_16x16x32_bf16 v[16:19], v[78:81], v[96:99], v[16:19]
	v_mfma_f32_16x16x32_bf16 v[12:15], v[70:73], v[104:107], v[12:15]
	v_mfma_f32_16x16x32_bf16 v[8:11], v[78:81], v[104:107], v[8:11]
	v_mfma_f32_16x16x32_bf16 v[4:7], v[70:73], v[112:115], v[4:7]
	v_mfma_f32_16x16x32_bf16 v[0:3], v[78:81], v[112:115], v[0:3]
	v_mfma_f32_16x16x32_bf16 v[28:31], v[74:77], v[92:95], v[28:31]
	v_mfma_f32_16x16x32_bf16 v[24:27], v[84:87], v[92:95], v[24:27]
	v_mfma_f32_16x16x32_bf16 v[20:23], v[74:77], v[100:103], v[20:23]
	v_mfma_f32_16x16x32_bf16 v[16:19], v[84:87], v[100:103], v[16:19]
	v_mfma_f32_16x16x32_bf16 v[12:15], v[74:77], v[108:111], v[12:15]
	v_mfma_f32_16x16x32_bf16 v[8:11], v[84:87], v[108:111], v[8:11]
	v_mfma_f32_16x16x32_bf16 v[4:7], v[74:77], v[116:119], v[4:7]
	v_mfma_f32_16x16x32_bf16 v[0:3], v[84:87], v[116:119], v[0:3]
	s_setprio 0
	s_barrier
	s_add_i32 s55, 0, 0x18000
	v_add_u32_e32 v84, s55, v82
	ds_read_b128 v[70:73], v84
	ds_read_b128 v[74:77], v84 offset:1024
	ds_read_b128 v[78:81], v84 offset:2048
	ds_read_b128 v[84:87], v84 offset:3072
	s_add_u32 s18, s38, 0xb0000
	s_addc_u32 s19, s39, 0
	s_mov_b32 m0, s58
	v_lshl_add_u64 v[128:129], s[18:19], 0, v[164:165]
	ds_read_b128 v[88:91], v83 offset:32768
	ds_read_b128 v[92:95], v83 offset:33792
	ds_read_b128 v[96:99], v83 offset:34816
	ds_read_b128 v[100:103], v83 offset:35840
	ds_read_b128 v[104:107], v83 offset:36864
	ds_read_b128 v[108:111], v83 offset:37888
	ds_read_b128 v[112:115], v83 offset:38912
	ds_read_b128 v[116:119], v83 offset:39936
	global_load_lds_dwordx4 v[128:129], off
	v_lshl_add_u64 v[128:129], s[18:19], 0, v[64:65]
	s_mov_b32 m0, s59
	s_nop 0
	global_load_lds_dwordx4 v[128:129], off
	s_waitcnt vmcnt(6)
	s_waitcnt lgkmcnt(0)
	s_barrier
	s_setprio 1
	s_waitcnt lgkmcnt(0)
	v_mfma_f32_16x16x32_bf16 v[60:63], v[70:73], v[88:91], v[60:63]
	v_mfma_f32_16x16x32_bf16 v[56:59], v[78:81], v[88:91], v[56:59]
	v_mfma_f32_16x16x32_bf16 v[52:55], v[70:73], v[96:99], v[52:55]
	v_mfma_f32_16x16x32_bf16 v[48:51], v[78:81], v[96:99], v[48:51]
	v_mfma_f32_16x16x32_bf16 v[44:47], v[70:73], v[104:107], v[44:47]
	v_mfma_f32_16x16x32_bf16 v[40:43], v[78:81], v[104:107], v[40:43]
	v_mfma_f32_16x16x32_bf16 v[36:39], v[70:73], v[112:115], v[36:39]
	v_mfma_f32_16x16x32_bf16 v[32:35], v[78:81], v[112:115], v[32:35]
	v_mfma_f32_16x16x32_bf16 v[60:63], v[74:77], v[92:95], v[60:63]
	v_mfma_f32_16x16x32_bf16 v[56:59], v[84:87], v[92:95], v[56:59]
	v_mfma_f32_16x16x32_bf16 v[52:55], v[74:77], v[100:103], v[52:55]
	v_mfma_f32_16x16x32_bf16 v[48:51], v[84:87], v[100:103], v[48:51]
	v_mfma_f32_16x16x32_bf16 v[44:47], v[74:77], v[108:111], v[44:47]
	v_mfma_f32_16x16x32_bf16 v[40:43], v[84:87], v[108:111], v[40:43]
	v_mfma_f32_16x16x32_bf16 v[36:39], v[74:77], v[116:119], v[36:39]
	v_mfma_f32_16x16x32_bf16 v[32:35], v[84:87], v[116:119], v[32:35]
	s_setprio 0
	s_barrier
	s_add_i32 s18, s55, s47
	v_lshl_add_u64 v[120:121], v[120:121], 0, s[0:1]
	s_mov_b32 m0, s18
	ds_read_b128 v[88:91], v83 offset:49152
	ds_read_b128 v[92:95], v83 offset:50176
	ds_read_b128 v[96:99], v83 offset:51200
	ds_read_b128 v[100:103], v83 offset:52224
	ds_read_b128 v[104:107], v83 offset:53248
	ds_read_b128 v[108:111], v83 offset:54272
	ds_read_b128 v[112:115], v83 offset:55296
	ds_read_b128 v[116:119], v83 offset:56320
	global_load_lds_dwordx4 v[120:121], off
	v_lshl_add_u64 v[122:123], v[122:123], 0, s[0:1]
	s_add_i32 m0, s18, 0x2000
	s_nop 0
	global_load_lds_dwordx4 v[122:123], off
	v_lshl_add_u64 v[120:121], v[124:125], 0, s[0:1]
	s_mov_b32 m0, s72
	s_nop 0
	global_load_lds_dwordx4 v[120:121], off
	v_lshl_add_u64 v[120:121], v[126:127], 0, s[0:1]
	s_mov_b32 m0, s73
	s_nop 0
	global_load_lds_dwordx4 v[120:121], off
	s_waitcnt vmcnt(6)
	s_waitcnt lgkmcnt(0)
	s_barrier
	s_setprio 1
	s_waitcnt lgkmcnt(0)
	v_mfma_f32_16x16x32_bf16 v[28:31], v[70:73], v[88:91], v[28:31]
	v_mfma_f32_16x16x32_bf16 v[24:27], v[78:81], v[88:91], v[24:27]
	v_mfma_f32_16x16x32_bf16 v[20:23], v[70:73], v[96:99], v[20:23]
	v_mfma_f32_16x16x32_bf16 v[16:19], v[78:81], v[96:99], v[16:19]
	v_mfma_f32_16x16x32_bf16 v[12:15], v[70:73], v[104:107], v[12:15]
	v_mfma_f32_16x16x32_bf16 v[8:11], v[78:81], v[104:107], v[8:11]
	v_mfma_f32_16x16x32_bf16 v[4:7], v[70:73], v[112:115], v[4:7]
	v_mfma_f32_16x16x32_bf16 v[0:3], v[78:81], v[112:115], v[0:3]
	v_mfma_f32_16x16x32_bf16 v[28:31], v[74:77], v[92:95], v[28:31]
	v_mfma_f32_16x16x32_bf16 v[24:27], v[84:87], v[92:95], v[24:27]
	v_mfma_f32_16x16x32_bf16 v[20:23], v[74:77], v[100:103], v[20:23]
	v_mfma_f32_16x16x32_bf16 v[16:19], v[84:87], v[100:103], v[16:19]
	v_mfma_f32_16x16x32_bf16 v[12:15], v[74:77], v[108:111], v[12:15]
	v_mfma_f32_16x16x32_bf16 v[8:11], v[84:87], v[108:111], v[8:11]
	v_mfma_f32_16x16x32_bf16 v[4:7], v[74:77], v[116:119], v[4:7]
	v_mfma_f32_16x16x32_bf16 v[0:3], v[84:87], v[116:119], v[0:3]
	s_setprio 0
	s_barrier
	s_add_u32 s52, s52, 0x100
	s_addc_u32 s53, s53, 0
	s_cmp_ge_i32 s54, vcc_lo
	s_mov_b64 s[18:19], s[34:35]
	s_mov_b32 s38, s54
	s_cbranch_scc0 .LBB0_284
	v_pk_add_f32 v[78:79], v[62:63], 0 op_sel_hi:[1,0]
	v_pk_add_f32 v[80:81], v[60:61], 0 op_sel_hi:[1,0]
	v_pk_add_f32 v[74:75], v[58:59], 0 op_sel_hi:[1,0]
	v_pk_add_f32 v[76:77], v[56:57], 0 op_sel_hi:[1,0]
	v_pk_add_f32 v[62:63], v[54:55], 0 op_sel_hi:[1,0]
	v_pk_add_f32 v[70:71], v[52:53], 0 op_sel_hi:[1,0]
	v_pk_add_f32 v[56:57], v[50:51], 0 op_sel_hi:[1,0]
	v_pk_add_f32 v[58:59], v[48:49], 0 op_sel_hi:[1,0]
	v_pk_add_f32 v[52:53], v[46:47], 0 op_sel_hi:[1,0]
	v_pk_add_f32 v[54:55], v[44:45], 0 op_sel_hi:[1,0]
	v_pk_add_f32 v[48:49], v[42:43], 0 op_sel_hi:[1,0]
	v_pk_add_f32 v[50:51], v[40:41], 0 op_sel_hi:[1,0]
	v_pk_add_f32 v[44:45], v[38:39], 0 op_sel_hi:[1,0]
	v_pk_add_f32 v[46:47], v[36:37], 0 op_sel_hi:[1,0]
	v_pk_add_f32 v[40:41], v[34:35], 0 op_sel_hi:[1,0]
	v_pk_add_f32 v[42:43], v[32:33], 0 op_sel_hi:[1,0]
	v_pk_add_f32 v[36:37], v[30:31], 0 op_sel_hi:[1,0]
	v_pk_add_f32 v[38:39], v[28:29], 0 op_sel_hi:[1,0]
	v_pk_add_f32 v[32:33], v[26:27], 0 op_sel_hi:[1,0]
	v_pk_add_f32 v[34:35], v[24:25], 0 op_sel_hi:[1,0]
	v_pk_add_f32 v[28:29], v[22:23], 0 op_sel_hi:[1,0]
	v_pk_add_f32 v[30:31], v[20:21], 0 op_sel_hi:[1,0]
	v_pk_add_f32 v[24:25], v[18:19], 0 op_sel_hi:[1,0]
	v_pk_add_f32 v[26:27], v[16:17], 0 op_sel_hi:[1,0]
	v_pk_add_f32 v[20:21], v[14:15], 0 op_sel_hi:[1,0]
	v_pk_add_f32 v[22:23], v[12:13], 0 op_sel_hi:[1,0]
	v_pk_add_f32 v[16:17], v[10:11], 0 op_sel_hi:[1,0]
	v_pk_add_f32 v[18:19], v[8:9], 0 op_sel_hi:[1,0]
	v_pk_add_f32 v[12:13], v[6:7], 0 op_sel_hi:[1,0]
	v_pk_add_f32 v[14:15], v[4:5], 0 op_sel_hi:[1,0]
	v_pk_add_f32 v[10:11], v[2:3], 0 op_sel_hi:[1,0]
	v_pk_add_f32 v[8:9], v[0:1], 0 op_sel_hi:[1,0]
	v_readlane_b32 s60, v239, 10
	v_readlane_b32 s61, v239, 11
	s_and_b64 vcc, exec, s[8:9]
	s_cbranch_vccz .LBB0_287
